# speedup vs baseline: 1.0616x; 1.0050x over previous
.LBB0_658:
	s_waitcnt vmcnt(0)
	v_add_f32_e32 v122, v140, v145
	s_waitcnt lgkmcnt(0)
	v_mul_f32_e64 v193, |v122|, s80
	v_exp_f32_e32 v193, v193
	v_min_f32_e32 v122, 0, v122
	s_and_b64 s[70:71], s[96:97], exec
	s_cselect_b32 s69, 0xb20, 0
	v_add_f32_e32 v196, 1.0, v193
	v_add_f32_e32 v194, -1.0, v196
	v_sub_f32_e32 v195, v194, v196
	v_sub_f32_e32 v194, v193, v194
	v_add_f32_e32 v195, 1.0, v195
	v_frexp_mant_f32_e32 v197, v196
	v_add_f32_e32 v198, v194, v195
	v_cvt_f64_f32_e32 v[194:195], v196
	v_frexp_exp_i32_f64_e32 v194, v[194:195]
	v_cmp_gt_f32_e32 vcc, s72, v197
	s_nop 1
	v_subbrev_co_u32_e32 v194, vcc, 0, v194, vcc
	v_sub_u32_e32 v195, 0, v194
	v_ldexp_f32 v196, v196, v195
	v_add_f32_e32 v197, -1.0, v196
	v_add_f32_e32 v200, 1.0, v196
	v_ldexp_f32 v195, v198, v195
	v_add_f32_e32 v198, 1.0, v197
	v_add_f32_e32 v201, -1.0, v200
	v_sub_f32_e32 v198, v196, v198
	v_sub_f32_e32 v196, v196, v201
	v_add_f32_e32 v198, v195, v198
	v_add_f32_e32 v195, v195, v196
	v_add_f32_e32 v196, v200, v195
	v_rcp_f32_e32 v201, v196
	v_add_f32_e32 v199, v197, v198
	v_sub_f32_e32 v197, v199, v197
	v_sub_f32_e32 v197, v198, v197
	v_sub_f32_e32 v198, v196, v200
	v_sub_f32_e32 v195, v195, v198
	v_mul_f32_e32 v198, v199, v201
	v_mul_f32_e32 v200, v196, v198
	v_fma_f32 v202, v198, v196, -v200
	v_fmac_f32_e32 v202, v198, v195
	v_add_f32_e32 v203, v200, v202
	v_sub_f32_e32 v204, v199, v203
	v_sub_f32_e32 v199, v199, v204
	v_sub_f32_e32 v200, v203, v200
	v_sub_f32_e32 v199, v199, v203
	v_add_f32_e32 v197, v197, v199
	v_sub_f32_e32 v199, v200, v202
	v_add_f32_e32 v197, v199, v197
	v_add_f32_e32 v199, v204, v197
	v_mul_f32_e32 v200, v201, v199
	v_mul_f32_e32 v202, v196, v200
	v_fma_f32 v196, v200, v196, -v202
	v_fmac_f32_e32 v196, v200, v195
	v_sub_f32_e32 v195, v204, v199
	v_add_f32_e32 v195, v197, v195
	v_add_f32_e32 v197, v202, v196
	v_sub_f32_e32 v203, v199, v197
	v_sub_f32_e32 v199, v199, v203
	v_sub_f32_e32 v202, v197, v202
	v_sub_f32_e32 v197, v199, v197
	v_add_f32_e32 v195, v195, v197
	v_sub_f32_e32 v196, v202, v196
	v_cvt_f32_i32_e32 v194, v194
	v_add_f32_e32 v195, v196, v195
	v_add_f32_e32 v196, v198, v200
	v_add_f32_e32 v195, v203, v195
	v_sub_f32_e32 v197, v196, v198
	v_mul_f32_e32 v195, v201, v195
	v_sub_f32_e32 v197, v200, v197
	v_add_f32_e32 v195, v197, v195
	v_mul_f32_e32 v200, 0x3f317218, v194
	v_add_f32_e32 v197, v196, v195
	v_fma_f32 v201, v194, s73, -v200
	v_mul_f32_e32 v198, v197, v197
	v_fmac_f32_e32 v201, 0xb102e308, v194
	v_sub_f32_e32 v194, v197, v196
	v_fmamk_f32 v199, v198, 0x3e9b6dac, v123
	v_sub_f32_e32 v194, v195, v194
	v_add_f32_e32 v195, v200, v201
	v_fmaak_f32 v199, v198, v199, 0x3f2aaada
	v_sub_f32_e32 v196, v195, v200
	v_ldexp_f32 v200, v197, 1
	v_mul_f32_e32 v197, v197, v198
	v_mul_f32_e32 v197, v197, v199
	v_add_f32_e32 v198, v200, v197
	v_sub_f32_e32 v199, v198, v200
	v_ldexp_f32 v194, v194, 1
	v_sub_f32_e32 v197, v197, v199
	v_add_f32_e32 v194, v194, v197
	v_add_f32_e32 v197, v198, v194
	v_sub_f32_e32 v198, v197, v198
	v_sub_f32_e32 v194, v194, v198
	v_add_f32_e32 v198, v195, v197
	v_sub_f32_e32 v199, v198, v195
	v_sub_f32_e32 v200, v198, v199
	v_sub_f32_e32 v196, v201, v196
	v_sub_f32_e32 v195, v195, v200
	v_sub_f32_e32 v197, v197, v199
	v_add_f32_e32 v195, v197, v195
	v_add_f32_e32 v197, v196, v194
	v_sub_f32_e32 v199, v197, v196
	v_sub_f32_e32 v200, v197, v199
	v_sub_f32_e32 v196, v196, v200
	v_sub_f32_e32 v194, v194, v199
	v_add_f32_e32 v195, v197, v195
	v_add_f32_e32 v194, v194, v196
	v_add_f32_e32 v196, v198, v195
	v_sub_f32_e32 v197, v196, v198
	v_sub_f32_e32 v195, v195, v197
	v_add_f32_e32 v194, v194, v195
	v_add_f32_e32 v194, v196, v194
	v_cmp_neq_f32_e32 vcc, s74, v193
	s_nop 1
	v_cndmask_b32_e32 v194, v126, v194, vcc
	v_cmp_ngt_f32_e32 vcc, -1.0, v193
	s_nop 1
	v_cndmask_b32_e32 v194, v127, v194, vcc
	v_cmp_neq_f32_e32 vcc, -1.0, v193
	s_nop 1
	v_cndmask_b32_e32 v194, v128, v194, vcc
	v_cmp_lt_f32_e64 vcc, |v193|, s75
	s_nop 1
	v_cndmask_b32_e32 v193, v194, v193, vcc
	v_sub_f32_e32 v122, v122, v193
	s_nop 1
	v_mov_b32_dpp v194, v122 row_shr:1 row_mask:0xf bank_mask:0xf bound_ctrl:0
	v_add_f32_e32 v122, v122, v194
	s_nop 1
	v_mov_b32_dpp v194, v122 row_shr:2 row_mask:0xf bank_mask:0xf bound_ctrl:0
	v_add_f32_e32 v122, v122, v194
	s_nop 1
	v_mov_b32_dpp v194, v122 row_shr:4 row_mask:0xf bank_mask:0xf bound_ctrl:0
	v_add_f32_e32 v122, v122, v194
	s_nop 1
	v_mov_b32_dpp v194, v122 row_shr:8 row_mask:0xf bank_mask:0xf bound_ctrl:0
	v_add_f32_e32 v122, v122, v194
	v_mov_b32_e32 v194, 0
	s_nop 1
	v_mov_b32_dpp v194, v122 row_bcast:15 row_mask:0xa bank_mask:0xf
	v_add_f32_e32 v122, v122, v194
	v_mov_b32_e32 v194, 0
	s_nop 1
	v_mov_b32_dpp v194, v122 row_bcast:31 row_mask:0xc bank_mask:0xf
	v_add_f32_e32 v122, v122, v194
	v_add_f32_e32 v199, v139, v144
	v_sub_f32_e32 v199, v199, v122
	v_mov_b32_e32 v193, v199
	v_mov_b32_e32 v194, v193
	s_nop 1
	v_mov_b32_dpp v194, v193 row_shr:1 row_mask:0xf bank_mask:0xf
	v_max_f32_e32 v193, v193, v194
	v_mov_b32_e32 v194, v193
	s_nop 1
	v_mov_b32_dpp v194, v193 row_shr:2 row_mask:0xf bank_mask:0xf
	v_max_f32_e32 v193, v193, v194
	v_mov_b32_e32 v194, v193
	s_nop 1
	v_mov_b32_dpp v194, v193 row_shr:4 row_mask:0xf bank_mask:0xf
	v_max_f32_e32 v193, v193, v194
	v_mov_b32_e32 v194, v193
	s_nop 1
	v_mov_b32_dpp v194, v193 row_shr:8 row_mask:0xf bank_mask:0xf
	v_max_f32_e32 v193, v193, v194
	v_mov_b32_e32 v194, v193
	s_nop 1
	v_mov_b32_dpp v194, v193 row_bcast:15 row_mask:0xa bank_mask:0xf
	v_max_f32_e32 v193, v193, v194
	v_mov_b32_e32 v194, v193
	s_nop 1
	v_mov_b32_dpp v194, v193 row_bcast:31 row_mask:0xc bank_mask:0xf
	v_max_f32_e32 v193, v193, v194
	v_add_u32_e32 v198, s69, v168
	v_max_f32_e32 v193, v193, v193
	v_max_f32_e32 v194, v142, v142
	v_max_f32_e32 v194, v194, v193
	ds_bpermute_b32 v193, v134, v194
	v_add_f32_e32 v122, v122, v194
	v_sub_f32_e32 v195, v142, v194
	v_mul_f32_e32 v195, 0x3fb8aa3b, v195
	v_mul_f32_e32 v196, 0xbfb8aa3b, v122
	s_waitcnt lgkmcnt(0)
	v_sub_f32_e32 v197, v199, v193
	v_exp_f32_e32 v195, v195
	v_exp_f32_e32 v196, v196
	v_mul_f32_e32 v197, 0x3fb8aa3b, v197
	v_exp_f32_e32 v197, v197
	ds_write2st64_b32 v198, v199, v194 offset1:1
	ds_write2st64_b32 v198, v195, v196 offset0:2 offset1:3
	ds_write_b32 v198, v197 offset:1024
	s_and_saveexec_b64 s[76:77], s[16:17]
	s_cbranch_execz .LBB0_660
	v_sub_f32_e32 v142, v142, v193
	v_mul_f32_e32 v142, 0x3fb8aa3b, v142
	v_exp_f32_e32 v142, v142
	s_and_b64 s[70:71], s[96:97], exec
	s_cselect_b32 s69, s81, 0x26b00
	v_mov_b32_e32 v193, s69
	ds_write_b32 v193, v142
